# attention loop: one workgroup barrier per half-step (second barrier dropped; each wave drains its LDS writes before the remaining barrier; loop exit keeps drain+barrier)
# baseline (speedup 1.0000x reference)
; __device__ __forceinline__ void partialSM(f32x16& p0, f32x16& p1, float& m_reg, float& mn, float& alpha) {
;     ...
;     constexpr float C2 = 1.4426950408889634f * SCALE;
;     if (__builtin_expect(__all((pmax - m_reg) * SCALE <= THR), 1)) { mn = m_reg; alpha = 1.f; }
;     else { mn = fmaxf(m_reg, pmax); alpha = __builtin_amdgcn_exp2f((m_reg - mn) * C2); m_reg = mn; }
;     const float mnL = -mn * C2;
; #pragma unroll
;     for (int r = 0; r < 16; ++r) p0[r] = fmaf(p0[r], C2, mnL);
; #pragma unroll
;     for (int r = 0; r < 16; ++r) p1[r] = fmaf(p1[r], C2, mnL);
; #pragma unroll
;     for (int r = 0; r < 16; ++r) p0[r] = __builtin_amdgcn_exp2f(p0[r]);
.Lp5_b1fast:
	s_waitcnt lgkmcnt(0)
	s_barrier
	s_waitcnt vmcnt(0)
	v_cndmask_b32_e64 v208, v96, 1.0, s[6:7]
	s_not_b64 vcc, s[6:7]
	ds_write_b128 v197, v[130:133]
	ds_write_b128 v198, v[134:137]
	s_cbranch_vccz .LBB0_1303
	s_and_saveexec_b64 s[36:37], s[0:1]
	ds_write_b32 v185, v208 offset:128
	s_or_b64 exec, exec, s[36:37]
	s_waitcnt lgkmcnt(0)
	ds_read_b128 v[150:153], v183 offset:224
	ds_read_b128 v[154:157], v183 offset:192
	ds_read_b128 v[158:161], v183 offset:160
	ds_read_b128 v[172:175], v183 offset:128
	s_waitcnt lgkmcnt(3)
	v_pk_mul_f32 v[16:17], v[16:17], v[152:153]
	s_waitcnt lgkmcnt(2)
	v_pk_mul_f32 v[12:13], v[12:13], v[156:157]
	s_waitcnt lgkmcnt(1)
	v_pk_mul_f32 v[8:9], v[8:9], v[160:161]
	s_waitcnt lgkmcnt(0)
	v_pk_mul_f32 v[4:5], v[4:5], v[174:175]
	v_pk_mul_f32 v[14:15], v[14:15], v[150:151]
	v_pk_mul_f32 v[10:11], v[10:11], v[154:155]
	v_pk_mul_f32 v[6:7], v[6:7], v[158:159]
	v_pk_mul_f32 v[2:3], v[2:3], v[172:173]
	v_pk_mul_f32 v[64:65], v[64:65], v[152:153]
	v_pk_mul_f32 v[60:61], v[60:61], v[156:157]
	v_pk_mul_f32 v[56:57], v[56:57], v[160:161]
	v_pk_mul_f32 v[52:53], v[52:53], v[174:175]
	v_pk_mul_f32 v[62:63], v[62:63], v[150:151]
	v_pk_mul_f32 v[58:59], v[58:59], v[154:155]
	v_pk_mul_f32 v[54:55], v[54:55], v[158:159]
	v_pk_mul_f32 v[50:51], v[50:51], v[172:173]
	v_pk_mul_f32 v[48:49], v[48:49], v[152:153]
	v_pk_mul_f32 v[44:45], v[44:45], v[156:157]
	v_pk_mul_f32 v[40:41], v[40:41], v[160:161]
	v_pk_mul_f32 v[36:37], v[36:37], v[174:175]
	v_pk_mul_f32 v[46:47], v[46:47], v[150:151]
	v_pk_mul_f32 v[42:43], v[42:43], v[154:155]
	v_pk_mul_f32 v[38:39], v[38:39], v[158:159]
	v_pk_mul_f32 v[34:35], v[34:35], v[172:173]
	v_pk_mul_f32 v[32:33], v[32:33], v[152:153]
	v_pk_mul_f32 v[28:29], v[28:29], v[156:157]
	v_pk_mul_f32 v[24:25], v[24:25], v[160:161]
	v_pk_mul_f32 v[20:21], v[20:21], v[174:175]
	v_pk_mul_f32 v[30:31], v[30:31], v[150:151]
	v_pk_mul_f32 v[26:27], v[26:27], v[154:155]
	v_pk_mul_f32 v[22:23], v[22:23], v[158:159]
	v_pk_mul_f32 v[18:19], v[18:19], v[172:173]
.LBB0_1303:
	v_cndmask_b32_e64 v206, v94, v206, s[6:7]
	v_mul_f32_e32 v207, 0xbe0293ee, v206
	v_fmamk_f32 v94, v146, 0x3e0293ee, v207
	v_fmamk_f32 v82, v82, 0x3e0293ee, v207
	v_fmamk_f32 v83, v83, 0x3e0293ee, v207
	v_fmamk_f32 v95, v147, 0x3e0293ee, v207
	v_fmamk_f32 v96, v148, 0x3e0293ee, v207
	v_fmamk_f32 v97, v149, 0x3e0293ee, v207
	v_fmamk_f32 v87, v87, 0x3e0293ee, v207
	v_fmamk_f32 v88, v88, 0x3e0293ee, v207
	v_fmamk_f32 v89, v89, 0x3e0293ee, v207
	v_fmamk_f32 v90, v90, 0x3e0293ee, v207
	v_fmamk_f32 v91, v91, 0x3e0293ee, v207
	v_fmamk_f32 v92, v92, 0x3e0293ee, v207
	v_fmamk_f32 v93, v93, 0x3e0293ee, v207
	v_fmamk_f32 v79, v79, 0x3e0293ee, v207
	v_fmamk_f32 v80, v80, 0x3e0293ee, v207
	v_fmamk_f32 v81, v81, 0x3e0293ee, v207
	v_exp_f32_e32 v146, v94
	v_exp_f32_e32 v147, v82
	v_exp_f32_e32 v148, v83
	v_exp_f32_e32 v159, v95
	v_exp_f32_e32 v160, v96
	v_exp_f32_e32 v161, v97
	v_exp_f32_e32 v149, v87
	v_exp_f32_e32 v158, v88
	v_exp_f32_e32 v150, v89
	v_exp_f32_e32 v151, v90
	v_exp_f32_e32 v155, v91
	v_exp_f32_e32 v157, v92
	v_exp_f32_e32 v152, v93
	v_exp_f32_e32 v153, v79
	v_exp_f32_e32 v154, v80
	v_exp_f32_e32 v156, v81
	v_fmamk_f32 v210, v71, 0x3e0293ee, v207
	v_fmamk_f32 v209, v78, 0x3e0293ee, v207
	v_fmamk_f32 v217, v66, 0x3e0293ee, v207
	v_fmamk_f32 v218, v67, 0x3e0293ee, v207
	v_fmamk_f32 v219, v68, 0x3e0293ee, v207
	v_fmamk_f32 v220, v69, 0x3e0293ee, v207
	v_fmamk_f32 v221, v70, 0x3e0293ee, v207
	v_fmamk_f32 v211, v72, 0x3e0293ee, v207
	v_fmamk_f32 v212, v84, 0x3e0293ee, v207
	v_fmamk_f32 v213, v85, 0x3e0293ee, v207
	v_fmamk_f32 v214, v86, 0x3e0293ee, v207
	v_fmamk_f32 v215, v76, 0x3e0293ee, v207
	v_fmamk_f32 v216, v77, 0x3e0293ee, v207
	v_fmamk_f32 v222, v73, 0x3e0293ee, v207
	v_fmamk_f32 v223, v74, 0x3e0293ee, v207
	v_fmac_f32_e32 v207, 0x3e0293ee, v75
	global_load_dwordx2 v[228:229], v179, s[68:69]
	s_add_i32 s98, s82, 2
	s_cmp_gt_u32 s98, s81
	s_cbranch_scc1 .Lp5_a2
	s_add_u32 s98, s16, 0x60000
	s_addc_u32 s99, s17, 0
	global_load_dwordx4 v[130:133], v188, s[98:99]
	s_add_u32 s98, s16, 0x70000
	s_addc_u32 s99, s17, 0
	global_load_dwordx4 v[134:137], v188, s[98:99]
	s_add_u32 s98, s100, 0x60000
	s_addc_u32 s99, s101, 0
	global_load_dwordx4 v[138:141], v188, s[98:99]
	s_add_u32 s98, s100, 0x70000
	s_addc_u32 s99, s101, 0
	global_load_dwordx4 v[142:145], v188, s[98:99]

; __device__ __forceinline__ void partialSM(f32x16& p0, f32x16& p1, float& m_reg, float& mn, float& alpha) {
;     ...
;     { auto rr = __builtin_amdgcn_permlane32_swap(__float_as_uint(pmax), __float_as_uint(pmax), false, false);
;       pmax = fmaxf(__uint_as_float(rr[0]), __uint_as_float(rr[1])); }
;     constexpr float C2 = 1.4426950408889634f * SCALE;
;     if (__builtin_expect(__all((pmax - m_reg) * SCALE <= THR), 1)) { mn = m_reg; alpha = 1.f; }
;     else { mn = fmaxf(m_reg, pmax); alpha = __builtin_amdgcn_exp2f((m_reg - mn) * C2); m_reg = mn; }
.Lp5_kw2_skip:
	s_nop 1
	v_permlane32_swap_b32_e32 v76, v77
	v_max_f32_e32 v76, v76, v77
	v_sub_f32_e32 v77, v76, v206
	v_mul_f32_e32 v77, 0x3db504f3, v77
	v_cmp_ge_f32_e32 vcc, s75, v77
	s_cmp_eq_u64 vcc, exec
	s_cselect_b64 s[6:7], -1, 0
	s_andn2_b64 vcc, exec, s[36:37]
	s_waitcnt lgkmcnt(0)
	s_barrier
	s_cbranch_vccnz .LBB0_1307
	s_waitcnt vmcnt(0)
	ds_write_b128 v197, v[130:133] offset:16384
	ds_write_b128 v198, v[134:137] offset:16384

; __device__ __forceinline__ void partialSM(f32x16& p0, f32x16& p1, float& m_reg, float& mn, float& alpha) {
;     ...
;     constexpr float C2 = 1.4426950408889634f * SCALE;
;     if (__builtin_expect(__all((pmax - m_reg) * SCALE <= THR), 1)) { mn = m_reg; alpha = 1.f; }
;     else { mn = fmaxf(m_reg, pmax); alpha = __builtin_amdgcn_exp2f((m_reg - mn) * C2); m_reg = mn; }
;     const float mnL = -mn * C2;
; #pragma unroll
;     for (int r = 0; r < 16; ++r) p0[r] = fmaf(p0[r], C2, mnL);
; #pragma unroll
;     for (int r = 0; r < 16; ++r) p1[r] = fmaf(p1[r], C2, mnL);
; #pragma unroll
;     for (int r = 0; r < 16; ++r) p0[r] = __builtin_amdgcn_exp2f(p0[r]);
; __device__ __forceinline__ void attn_block(const BlockRef& cur, const BlockRef& nxt, char* lds, Seam& S) {
;     ...
;     for (int t = 1; t + 1 < NT; t += 2) {
;         HALF_STEP(pB0, pB1, mnB, alB, pA0, pA1, alA, t, 1, 0, 0);
;         HALF_STEP(pA0, pA1, mnA, alA, pB0, pB1, alB, t + 1, 0, 1, 1);
;     }
.LBB0_1311:
	v_cndmask_b32_e64 v206, v76, v206, s[6:7]
	v_mul_f32_e32 v76, 0xbe0293ee, v206
	v_mov_b32_e32 v131, v76
	v_fmamk_f32 v77, v192, 0x3e0293ee, v76
	v_fmamk_f32 v78, v146, 0x3e0293ee, v76
	v_fmamk_f32 v79, v147, 0x3e0293ee, v76
	v_fmamk_f32 v80, v148, 0x3e0293ee, v76
	v_fmamk_f32 v81, v149, 0x3e0293ee, v76
	v_fmamk_f32 v130, v150, 0x3e0293ee, v76
	v_fmamk_f32 v88, v88, 0x3e0293ee, v76
	v_fmamk_f32 v89, v89, 0x3e0293ee, v76
	v_fmamk_f32 v90, v90, 0x3e0293ee, v76
	v_fmamk_f32 v91, v91, 0x3e0293ee, v76
	v_fmamk_f32 v92, v92, 0x3e0293ee, v76
	v_fmamk_f32 v93, v93, 0x3e0293ee, v76
	v_fmamk_f32 v94, v94, 0x3e0293ee, v76
	v_fmamk_f32 v95, v95, 0x3e0293ee, v76
	v_fmamk_f32 v96, v96, 0x3e0293ee, v76
	v_fmac_f32_e32 v131, 0x3e0293ee, v97
	v_exp_f32_e32 v219, v77
	v_exp_f32_e32 v220, v78
	v_exp_f32_e32 v221, v79
	v_exp_f32_e32 v222, v80
	v_exp_f32_e32 v223, v81
	v_exp_f32_e32 v225, v130
	v_exp_f32_e32 v224, v88
	v_exp_f32_e32 v226, v89
	v_exp_f32_e32 v211, v90
	v_exp_f32_e32 v212, v91
	v_exp_f32_e32 v213, v92
	v_exp_f32_e32 v215, v93
	v_exp_f32_e32 v214, v94
	v_exp_f32_e32 v216, v95
	v_exp_f32_e32 v217, v96
	v_exp_f32_e32 v218, v131
	v_pk_fma_f32 v[194:195], v[66:67], s[14:15], v[76:77] op_sel_hi:[1,0,0]
	v_fmac_f32_e32 v181, v177, v205
	v_pk_fma_f32 v[192:193], v[82:83], s[14:15], v[76:77] op_sel_hi:[1,0,0]
	v_pk_fma_f32 v[158:159], v[84:85], s[14:15], v[76:77] op_sel_hi:[1,0,0]
	v_pk_fma_f32 v[154:155], v[86:87], s[14:15], v[76:77] op_sel_hi:[1,0,0]
	v_pk_fma_f32 v[150:151], v[74:75], s[14:15], v[76:77] op_sel_hi:[1,0,0]
	v_pk_fma_f32 v[160:161], v[68:69], s[14:15], v[76:77] op_sel_hi:[1,0,0]
	v_pk_fma_f32 v[156:157], v[70:71], s[14:15], v[76:77] op_sel_hi:[1,0,0]
	v_pk_fma_f32 v[152:153], v[72:73], s[14:15], v[76:77] op_sel_hi:[1,0,0]
	v_fma_f32 v205, v181, v208, v209
	v_add_u32_e32 v179, 16, v179
	s_add_u32 s16, s16, 0x40000
	s_addc_u32 s17, s17, 0
	s_add_u32 s100, s100, 0x40000
	s_addc_u32 s101, s101, 0
	s_cmp_ge_u32 s82, s81
	s_cbranch_scc1 .Lp5_exit
	v_mov_b32_e32 v177, v207
	s_branch .LBB0_1299

; #define SBAR() __builtin_amdgcn_sched_barrier(0)
; __device__ __forceinline__ void attn_block(const BlockRef& cur, const BlockRef& nxt, char* lds, Seam& S) {
;     ...
;     for (int t = 1; t + 1 < NT; t += 2) {
;         HALF_STEP(pB0, pB1, mnB, alB, pA0, pA1, alA, t, 1, 0, 0);
;         HALF_STEP(pA0, pA1, mnA, alA, pB0, pB1, alB, t + 1, 0, 1, 1);
;     }
;     mw = LDMASK(NT - 1);
;     SBAR(); qkt<1>(pB0, pB1, K_lds, r32, hi, S.qr); SBAR();
.Lp5_exit:
	s_waitcnt lgkmcnt(0)
	s_barrier
